# static priority raise (s_setprio 1) for waves 4-7 over the whole diff-attention fast loop, reset in the exit stubs
# speedup vs baseline: 1.0042x; 1.0013x over previous
; #define WAIT_BAR(N) asm volatile("s_waitcnt vmcnt(" #N ") lgkmcnt(0)\n\ts_barrier":::"memory")
;   #define RESC() do{ if(resc){ asm volatile("s_waitcnt lgkmcnt(0)":::"memory"); \
;       _Pragma("unroll") for(int d_=0;d_<2;++d_) _Pragma("unroll") for(int r=0;r<16;++r)o[d_][r]*=wsf[crow(r,hi)]; } }while(0)
;   #define ROT() do{sl_prev=sl_cur;sl_cur=sl_next;sl_next=(sl_next==(NSLOT-1)*SLOTB)?0:sl_next+SLOTB;}while(0)
;     ...
;   for(;t+5<NT;t+=2){
;     STEP(pB0,pB1,pA0,pA1,t,true,true,true);     WAIT_BAR(2); RESC(); ROT();
;     STEP(pA0,pA1,pB0,pB1,t+1,true,true,true);   WAIT_BAR(2); RESC(); ROT();
;   }
.Lfb_pre:
	v_readfirstlane_b32 s0, v230
	s_nop 3
	s_lshr_b32 s0, s0, 6
	s_cmp_ge_u32 s0, 4
	s_cbranch_scc0 .Lfb_noprio
	s_setprio 1

; #define WAIT_BAR(N) asm volatile("s_waitcnt vmcnt(" #N ") lgkmcnt(0)\n\ts_barrier":::"memory")
;   #define RESC() do{ if(resc){ asm volatile("s_waitcnt lgkmcnt(0)":::"memory"); \
;       _Pragma("unroll") for(int d_=0;d_<2;++d_) _Pragma("unroll") for(int r=0;r<16;++r)o[d_][r]*=wsf[crow(r,hi)]; } }while(0)
;   #define ROT() do{sl_prev=sl_cur;sl_cur=sl_next;sl_next=(sl_next==(NSLOT-1)*SLOTB)?0:sl_next+SLOTB;}while(0)
;     ...
;   int t=1;
;     ...
;   for(;t+5<NT;t+=2){
;     STEP(pB0,pB1,pA0,pA1,t,true,true,true);     WAIT_BAR(2); RESC(); ROT();
;     STEP(pA0,pA1,pB0,pB1,t+1,true,true,true);   WAIT_BAR(2); RESC(); ROT();
;   }
.Lfb_even_s2:
	v_mfma_f32_32x32x16_bf16 v[64:79], v[60:63], v[134:137], v[32:47]
	v_add_u32_e32 v196, s24, v211
	ds_read_b64_tr_b16 v[150:151], v196 offset:24576
	ds_read_b64_tr_b16 v[152:153], v196 offset:25088
	v_add_f32_e32 v222, v96, v222
	v_add_f32_e32 v222, v97, v222
	v_add_f32_e32 v222, v98, v222
	v_add_f32_e32 v222, v99, v222
	v_add_f32_e32 v222, v100, v222
	v_add_f32_e32 v222, v101, v222
	v_cvt_pk_bf16_f32 v142, v96, v97
	v_cvt_pk_bf16_f32 v143, v98, v99
	ds_read_b64_tr_b16 v[146:147], v196 offset:28672
	ds_read_b64_tr_b16 v[148:149], v196 offset:29184
	v_add_f32_e32 v222, v102, v222
	v_add_f32_e32 v222, v103, v222
	v_add_f32_e32 v222, v104, v222
	v_add_f32_e32 v222, v105, v222
	v_mfma_f32_32x32x16_bf16 v[48:63], v[174:177], v[134:137], v[32:47]
	v_cvt_pk_bf16_f32 v144, v100, v101
	v_cvt_pk_bf16_f32 v145, v102, v103
	ds_read_b64_tr_b16 v[96:97], v196 offset:25600
	ds_read_b64_tr_b16 v[98:99], v196 offset:26112
	v_mfma_f32_32x32x16_bf16 v[64:79], v[178:181], v[122:125], v[64:79]
	v_add_f32_e32 v222, v106, v222
	v_add_f32_e32 v222, v107, v222
	v_add_f32_e32 v222, v108, v222
	v_add_f32_e32 v222, v109, v222
	v_cvt_pk_bf16_f32 v138, v104, v105
	v_cvt_pk_bf16_f32 v139, v106, v107
	ds_read_b64_tr_b16 v[100:101], v196 offset:29696
	ds_read_b64_tr_b16 v[102:103], v196 offset:30208
	v_mfma_f32_32x32x16_bf16 v[48:63], v[170:173], v[122:125], v[48:63]
	v_exp_f32_e32 v89, v89
	v_add_f32_e32 v222, v110, v222
	v_add_f32_e32 v222, v111, v222
	v_cvt_pk_bf16_f32 v140, v108, v109
	v_cvt_pk_bf16_f32 v141, v110, v111
	ds_read_b64_tr_b16 v[104:105], v196 offset:26624
	ds_read_b64_tr_b16 v[106:107], v196 offset:27136
	v_mfma_f32_32x32x16_bf16 v[64:79], v[166:169], v[118:121], v[64:79]
	v_exp_f32_e32 v90, v90
	v_exp_f32_e32 v91, v91
	v_cvt_pk_bf16_f32 v130, v80, v81
	v_cvt_pk_bf16_f32 v131, v82, v83
	ds_read_b64_tr_b16 v[80:81], v196 offset:30720
	ds_read_b64_tr_b16 v[82:83], v196 offset:31232
	v_mfma_f32_32x32x16_bf16 v[48:63], v[162:165], v[118:121], v[48:63]
	v_exp_f32_e32 v92, v92
	v_exp_f32_e32 v93, v93
	v_cvt_pk_bf16_f32 v132, v84, v85
	v_cvt_pk_bf16_f32 v133, v86, v87
	ds_read_b64_tr_b16 v[84:85], v196 offset:27648
	ds_read_b64_tr_b16 v[86:87], v196 offset:28160
	v_mfma_f32_32x32x16_bf16 v[64:79], v[158:161], v[114:117], v[64:79]
	v_exp_f32_e32 v94, v94
	v_exp_f32_e32 v95, v95
	v_cvt_pk_bf16_f32 v126, v88, v89
	v_cvt_pk_bf16_f32 v127, v90, v91
	ds_read_b64_tr_b16 v[88:89], v196 offset:31744
	ds_read_b64_tr_b16 v[90:91], v196 offset:32256
	v_mfma_f32_32x32x16_bf16 v[48:63], v[154:157], v[114:117], v[48:63]
	v_cvt_pk_bf16_f32 v128, v92, v93
	v_cvt_pk_bf16_f32 v129, v94, v95
	s_add_i32 m0, s13, s69
	s_nop 0
	global_load_lds_dwordx4 v188, s[2:3]
	s_add_i32 m0, s72, s70
	s_add_u32 s2, s2, 0x58000
	global_load_lds_dwordx4 v186, s[26:27]
	s_addc_u32 s3, s3, 0
	s_add_u32 s26, s26, 0x58000
	s_addc_u32 s27, s27, 0
	s_waitcnt lgkmcnt(8)
	v_mfma_f32_32x32x16_bf16 v[16:31], v[142:145], v[150:153], v[16:31]
	v_exp_f32_e32 v64, v64
	v_exp_f32_e32 v65, v65
	v_exp_f32_e32 v66, v66
	v_exp_f32_e32 v67, v67
	v_mfma_f32_32x32x16_bf16 v[0:15], v[142:145], v[146:149], v[0:15]
	v_exp_f32_e32 v68, v68
	v_exp_f32_e32 v69, v69
	v_exp_f32_e32 v70, v70
	v_add_u32_e32 v92, s72, v210
	ds_read_b128 v[174:177], v92
	ds_read_b128 v[170:173], v92 offset:512
	v_mfma_f32_32x32x16_bf16 v[16:31], v[138:141], v[96:99], v[16:31]
	v_exp_f32_e32 v71, v71
	v_exp_f32_e32 v72, v72
	v_exp_f32_e32 v73, v73
	ds_read_b128 v[166:169], v92 offset:2048
	ds_read_b128 v[162:165], v92 offset:2560
	v_mfma_f32_32x32x16_bf16 v[0:15], v[138:141], v[100:103], v[0:15]
	v_exp_f32_e32 v74, v74
	v_exp_f32_e32 v75, v75
	v_exp_f32_e32 v76, v76
	ds_read_b128 v[158:161], v92 offset:4096
	ds_read_b128 v[154:157], v92 offset:4608
	s_waitcnt lgkmcnt(6)
	v_mfma_f32_32x32x16_bf16 v[16:31], v[130:133], v[104:107], v[16:31]
	v_exp_f32_e32 v77, v77
	v_exp_f32_e32 v78, v78
	v_exp_f32_e32 v79, v79
	ds_read_b128 v[150:153], v92 offset:6144
	ds_read_b128 v[146:149], v92 offset:6656
	v_mfma_f32_32x32x16_bf16 v[0:15], v[130:133], v[80:83], v[0:15]
	v_exp_f32_e32 v48, v48
	v_exp_f32_e32 v49, v49
	v_exp_f32_e32 v50, v50
	v_mfma_f32_32x32x16_bf16 v[16:31], v[126:129], v[84:87], v[16:31]
	v_exp_f32_e32 v51, v51
	v_exp_f32_e32 v52, v52
	v_exp_f32_e32 v53, v53
	v_mfma_f32_32x32x16_bf16 v[0:15], v[126:129], v[88:91], v[0:15]
	v_exp_f32_e32 v54, v54
	v_exp_f32_e32 v55, v55
	v_exp_f32_e32 v56, v56
	s_add_i32 s0, s72, 0x2000
	s_cmpk_lg_i32 s72, 0x4000
	s_cselect_b32 s74, s0, 0
	s_add_i32 s0, s75, 2
	s_cmp_ge_u32 s0, s71
	s_mov_b32 s75, s0
	s_mov_b32 s0, s13
	s_mov_b32 s24, s72
	s_mov_b32 s13, s74
	s_waitcnt vmcnt(2) lgkmcnt(0)
	s_barrier
	s_cbranch_scc0 .Lfb_even
	s_mov_b32 s13, s0
	s_add_i32 s75, s75, -2
	v_mov_b32_e32 v223, v222
	s_setprio 0
	v_exp_f32_e32 v57, v57
	v_exp_f32_e32 v58, v58
	v_exp_f32_e32 v59, v59
	v_exp_f32_e32 v60, v60
	v_exp_f32_e32 v61, v61
	v_exp_f32_e32 v62, v62
	v_exp_f32_e32 v63, v63
	s_branch .LBB0_1231

; #define WAIT_BAR(N) asm volatile("s_waitcnt vmcnt(" #N ") lgkmcnt(0)\n\ts_barrier":::"memory")
;   #define RESC() do{ if(resc){ asm volatile("s_waitcnt lgkmcnt(0)":::"memory"); \
;       _Pragma("unroll") for(int d_=0;d_<2;++d_) _Pragma("unroll") for(int r=0;r<16;++r)o[d_][r]*=wsf[crow(r,hi)]; } }while(0)
;   #define ROT() do{sl_prev=sl_cur;sl_cur=sl_next;sl_next=(sl_next==(NSLOT-1)*SLOTB)?0:sl_next+SLOTB;}while(0)
;     ...
;   int t=1;
;     ...
;   for(;t+5<NT;t+=2){
;     STEP(pB0,pB1,pA0,pA1,t,true,true,true);     WAIT_BAR(2); RESC(); ROT();
;     STEP(pA0,pA1,pB0,pB1,t+1,true,true,true);   WAIT_BAR(2); RESC(); ROT();
;   }
.Lfb_odd_s2:
	v_mfma_f32_32x32x16_bf16 v[64:79], v[60:63], v[134:137], v[32:47]
	v_exp_f32_e32 v89, v89
	v_exp_f32_e32 v90, v90
	v_add_u32_e32 v196, s24, v211
	ds_read_b64_tr_b16 v[150:151], v196 offset:24576
	ds_read_b64_tr_b16 v[152:153], v196 offset:25088
	v_cvt_pk_bf16_f32 v142, v96, v97
	v_cvt_pk_bf16_f32 v143, v98, v99
	ds_read_b64_tr_b16 v[146:147], v196 offset:28672
	ds_read_b64_tr_b16 v[148:149], v196 offset:29184
	v_mfma_f32_32x32x16_bf16 v[48:63], v[174:177], v[134:137], v[32:47]
	v_exp_f32_e32 v91, v91
	v_exp_f32_e32 v92, v92
	v_cvt_pk_bf16_f32 v144, v100, v101
	v_cvt_pk_bf16_f32 v145, v102, v103
	ds_read_b64_tr_b16 v[96:97], v196 offset:25600
	ds_read_b64_tr_b16 v[98:99], v196 offset:26112
	v_mfma_f32_32x32x16_bf16 v[64:79], v[178:181], v[122:125], v[64:79]
	v_exp_f32_e32 v93, v93
	v_exp_f32_e32 v94, v94
	v_cvt_pk_bf16_f32 v138, v104, v105
	v_cvt_pk_bf16_f32 v139, v106, v107
	ds_read_b64_tr_b16 v[100:101], v196 offset:29696
	ds_read_b64_tr_b16 v[102:103], v196 offset:30208
	v_mfma_f32_32x32x16_bf16 v[48:63], v[170:173], v[122:125], v[48:63]
	v_exp_f32_e32 v95, v95
	v_add_f32_e32 v222, v80, v222
	v_add_f32_e32 v222, v81, v222
	v_cvt_pk_bf16_f32 v140, v108, v109
	v_cvt_pk_bf16_f32 v141, v110, v111
	ds_read_b64_tr_b16 v[104:105], v196 offset:26624
	ds_read_b64_tr_b16 v[106:107], v196 offset:27136
	v_mfma_f32_32x32x16_bf16 v[64:79], v[166:169], v[118:121], v[64:79]
	v_add_f32_e32 v222, v82, v222
	v_add_f32_e32 v222, v83, v222
	v_add_f32_e32 v222, v84, v222
	v_add_f32_e32 v222, v85, v222
	v_cvt_pk_bf16_f32 v130, v80, v81
	v_cvt_pk_bf16_f32 v131, v82, v83
	ds_read_b64_tr_b16 v[80:81], v196 offset:30720
	ds_read_b64_tr_b16 v[82:83], v196 offset:31232
	v_mfma_f32_32x32x16_bf16 v[48:63], v[162:165], v[118:121], v[48:63]
	v_add_f32_e32 v222, v86, v222
	v_add_f32_e32 v222, v87, v222
	v_add_f32_e32 v222, v88, v222
	v_add_f32_e32 v222, v89, v222
	v_cvt_pk_bf16_f32 v132, v84, v85
	v_cvt_pk_bf16_f32 v133, v86, v87
	ds_read_b64_tr_b16 v[84:85], v196 offset:27648
	ds_read_b64_tr_b16 v[86:87], v196 offset:28160
	v_mfma_f32_32x32x16_bf16 v[64:79], v[158:161], v[114:117], v[64:79]
	v_add_f32_e32 v222, v90, v222
	v_add_f32_e32 v222, v91, v222
	v_add_f32_e32 v222, v92, v222
	v_add_f32_e32 v222, v93, v222
	v_cvt_pk_bf16_f32 v126, v88, v89
	v_cvt_pk_bf16_f32 v127, v90, v91
	ds_read_b64_tr_b16 v[88:89], v196 offset:31744
	ds_read_b64_tr_b16 v[90:91], v196 offset:32256
	v_mfma_f32_32x32x16_bf16 v[48:63], v[154:157], v[114:117], v[48:63]
	v_add_f32_e32 v222, v94, v222
	v_add_f32_e32 v222, v95, v222
	v_cvt_pk_bf16_f32 v128, v92, v93
	v_cvt_pk_bf16_f32 v129, v94, v95
	s_add_i32 m0, s13, s69
	s_nop 0
	global_load_lds_dwordx4 v188, s[2:3]
	s_add_i32 m0, s72, s70
	s_add_u32 s2, s2, 0x58000
	global_load_lds_dwordx4 v186, s[26:27]
	s_addc_u32 s3, s3, 0
	s_add_u32 s26, s26, 0x58000
	s_addc_u32 s27, s27, 0
	s_waitcnt lgkmcnt(8)
	v_mfma_f32_32x32x16_bf16 v[16:31], v[142:145], v[150:153], v[16:31]
	v_exp_f32_e32 v64, v64
	v_exp_f32_e32 v65, v65
	v_exp_f32_e32 v66, v66
	v_exp_f32_e32 v67, v67
	v_mfma_f32_32x32x16_bf16 v[0:15], v[142:145], v[146:149], v[0:15]
	v_exp_f32_e32 v68, v68
	v_exp_f32_e32 v69, v69
	v_exp_f32_e32 v70, v70
	v_add_u32_e32 v92, s72, v210
	ds_read_b128 v[174:177], v92
	ds_read_b128 v[170:173], v92 offset:512
	v_mfma_f32_32x32x16_bf16 v[16:31], v[138:141], v[96:99], v[16:31]
	v_exp_f32_e32 v71, v71
	v_exp_f32_e32 v72, v72
	v_exp_f32_e32 v73, v73
	ds_read_b128 v[166:169], v92 offset:2048
	ds_read_b128 v[162:165], v92 offset:2560
	v_mfma_f32_32x32x16_bf16 v[0:15], v[138:141], v[100:103], v[0:15]
	v_exp_f32_e32 v74, v74
	v_exp_f32_e32 v75, v75
	v_exp_f32_e32 v76, v76
	ds_read_b128 v[158:161], v92 offset:4096
	ds_read_b128 v[154:157], v92 offset:4608
	s_waitcnt lgkmcnt(6)
	v_mfma_f32_32x32x16_bf16 v[16:31], v[130:133], v[104:107], v[16:31]
	v_exp_f32_e32 v77, v77
	v_exp_f32_e32 v78, v78
	v_exp_f32_e32 v79, v79
	ds_read_b128 v[150:153], v92 offset:6144
	ds_read_b128 v[146:149], v92 offset:6656
	v_mfma_f32_32x32x16_bf16 v[0:15], v[130:133], v[80:83], v[0:15]
	v_exp_f32_e32 v48, v48
	v_exp_f32_e32 v49, v49
	v_exp_f32_e32 v50, v50
	v_mfma_f32_32x32x16_bf16 v[16:31], v[126:129], v[84:87], v[16:31]
	v_exp_f32_e32 v51, v51
	v_exp_f32_e32 v52, v52
	v_exp_f32_e32 v53, v53
	v_mfma_f32_32x32x16_bf16 v[0:15], v[126:129], v[88:91], v[0:15]
	v_exp_f32_e32 v54, v54
	v_exp_f32_e32 v55, v55
	v_exp_f32_e32 v56, v56
	s_add_i32 s0, s72, 0x2000
	s_cmpk_lg_i32 s72, 0x4000
	s_cselect_b32 s74, s0, 0
	s_add_i32 s0, s75, 2
	s_cmp_ge_u32 s0, s71
	s_mov_b32 s75, s0
	s_mov_b32 s0, s13
	s_mov_b32 s24, s72
	s_mov_b32 s13, s74
	s_waitcnt vmcnt(2) lgkmcnt(0)
	s_barrier
	s_cbranch_scc0 .Lfb_odd
	s_mov_b32 s13, s0
	s_add_i32 s75, s75, -2
	v_mov_b32_e32 v223, v222
	s_setprio 0
	v_exp_f32_e32 v57, v57
	v_exp_f32_e32 v58, v58
	v_exp_f32_e32 v59, v59
	v_exp_f32_e32 v60, v60
	v_exp_f32_e32 v61, v61
	v_exp_f32_e32 v62, v62
	v_exp_f32_e32 v63, v63
	s_branch .LBB0_1231
